# conv main loop: fully unrolled 32-step schedule, LDS fragment reads issued two steps (8 MFMAs) ahead in a 3-deep register ring
# speedup vs baseline: 1.0079x; 1.0060x over previous
.LBB0_937:
	s_bitcmp1_b32 s57, 0
	s_cselect_b32 s26, 0x10400, 0
	s_add_i32 s26, s26, 0
	s_mov_b64 s[30:31], -1
	s_andn2_b64 vcc, exec, s[28:29]
	v_add_u32_e32 v1, s26, v196
	s_cbranch_vccnz .LBB0_941
	s_lshl_b32 s26, s57, 9
	v_mov_b64_e32 v[142:143], v[78:79]
	v_mov_b64_e32 v[126:127], v[62:63]
	v_mov_b64_e32 v[110:111], v[46:47]
	v_mov_b64_e32 v[94:95], v[30:31]
	s_mov_b32 s30, 0
	s_mov_b64 s[28:29], -1
	s_lshl_b32 s26, s26, 1
	v_mov_b64_e32 v[140:141], v[76:77]
	v_mov_b64_e32 v[138:139], v[74:75]
	v_mov_b64_e32 v[136:137], v[72:73]
	v_mov_b64_e32 v[134:135], v[70:71]
	v_mov_b64_e32 v[132:133], v[68:69]
	v_mov_b64_e32 v[130:131], v[66:67]
	v_mov_b64_e32 v[128:129], v[64:65]
	v_mov_b64_e32 v[124:125], v[60:61]
	v_mov_b64_e32 v[122:123], v[58:59]
	v_mov_b64_e32 v[120:121], v[56:57]
	v_mov_b64_e32 v[118:119], v[54:55]
	v_mov_b64_e32 v[116:117], v[52:53]
	v_mov_b64_e32 v[114:115], v[50:51]
	v_mov_b64_e32 v[112:113], v[48:49]
	v_mov_b64_e32 v[108:109], v[44:45]
	v_mov_b64_e32 v[106:107], v[42:43]
	v_mov_b64_e32 v[104:105], v[40:41]
	v_mov_b64_e32 v[102:103], v[38:39]
	v_mov_b64_e32 v[100:101], v[36:37]
	v_mov_b64_e32 v[98:99], v[34:35]
	v_mov_b64_e32 v[96:97], v[32:33]
	v_mov_b64_e32 v[92:93], v[28:29]
	v_mov_b64_e32 v[90:91], v[26:27]
	v_mov_b64_e32 v[88:89], v[24:25]
	v_mov_b64_e32 v[86:87], v[22:23]
	v_mov_b64_e32 v[84:85], v[20:21]
	v_mov_b64_e32 v[82:83], v[18:19]
	v_mov_b64_e32 v[80:81], v[16:17]
	v_add_u32_e32 v15, s26, v201
	ds_read_b128 v[2:5], v1 offset:16640
	ds_read_b128 v[10:13], v15 offset:8192
	ds_read_b128 v[216:219], v1 offset:49920
	ds_read_b128 v[224:227], v15 offset:7680
	ds_read_b128 v[6:9], v1 offset:16672
	ds_read_b128 v[212:215], v15 offset:8224
	ds_read_b128 v[220:223], v1 offset:49952
	ds_read_b128 v[228:231], v15 offset:7712
	ds_read_b128 v[244:247], v1 offset:16704
	ds_read_b128 v[232:235], v15 offset:8256
	ds_read_b128 v[248:251], v1 offset:49984
	ds_read_b128 v[236:239], v15 offset:7744
	s_waitcnt lgkmcnt(8)
	v_mfma_f32_32x32x16_bf16 v[128:143], v[10:13], v[2:5], v[128:143]
	v_mfma_f32_32x32x16_bf16 v[112:127], v[10:13], v[216:219], v[112:127]
	v_mfma_f32_32x32x16_bf16 v[96:111], v[224:227], v[2:5], v[96:111]
	v_mfma_f32_32x32x16_bf16 v[80:95], v[224:227], v[216:219], v[80:95]
	ds_read_b128 v[2:5], v1 offset:16736
	ds_read_b128 v[10:13], v15 offset:8288
	ds_read_b128 v[216:219], v1 offset:50016
	ds_read_b128 v[224:227], v15 offset:7776
	s_waitcnt lgkmcnt(8)
	v_mfma_f32_32x32x16_bf16 v[128:143], v[212:215], v[6:9], v[128:143]
	v_mfma_f32_32x32x16_bf16 v[112:127], v[212:215], v[220:223], v[112:127]
	v_mfma_f32_32x32x16_bf16 v[96:111], v[228:231], v[6:9], v[96:111]
	v_mfma_f32_32x32x16_bf16 v[80:95], v[228:231], v[220:223], v[80:95]
	ds_read_b128 v[6:9], v1 offset:16768
	ds_read_b128 v[212:215], v15 offset:8320
	ds_read_b128 v[220:223], v1 offset:50048
	ds_read_b128 v[228:231], v15 offset:7808
	s_waitcnt lgkmcnt(8)
	v_mfma_f32_32x32x16_bf16 v[128:143], v[232:235], v[244:247], v[128:143]
	v_mfma_f32_32x32x16_bf16 v[112:127], v[232:235], v[248:251], v[112:127]
	v_mfma_f32_32x32x16_bf16 v[96:111], v[236:239], v[244:247], v[96:111]
	v_mfma_f32_32x32x16_bf16 v[80:95], v[236:239], v[248:251], v[80:95]
	ds_read_b128 v[244:247], v1 offset:16800
	ds_read_b128 v[232:235], v15 offset:8352
	ds_read_b128 v[248:251], v1 offset:50080
	ds_read_b128 v[236:239], v15 offset:7840
	s_waitcnt lgkmcnt(8)
	v_mfma_f32_32x32x16_bf16 v[128:143], v[10:13], v[2:5], v[128:143]
	v_mfma_f32_32x32x16_bf16 v[112:127], v[10:13], v[216:219], v[112:127]
	v_mfma_f32_32x32x16_bf16 v[96:111], v[224:227], v[2:5], v[96:111]
	v_mfma_f32_32x32x16_bf16 v[80:95], v[224:227], v[216:219], v[80:95]
	ds_read_b128 v[2:5], v1 offset:16832
	ds_read_b128 v[10:13], v15 offset:8384
	ds_read_b128 v[216:219], v1 offset:50112
	ds_read_b128 v[224:227], v15 offset:7872
	s_waitcnt lgkmcnt(8)
	v_mfma_f32_32x32x16_bf16 v[128:143], v[212:215], v[6:9], v[128:143]
	v_mfma_f32_32x32x16_bf16 v[112:127], v[212:215], v[220:223], v[112:127]
	v_mfma_f32_32x32x16_bf16 v[96:111], v[228:231], v[6:9], v[96:111]
	v_mfma_f32_32x32x16_bf16 v[80:95], v[228:231], v[220:223], v[80:95]
	ds_read_b128 v[6:9], v1 offset:16864
	ds_read_b128 v[212:215], v15 offset:8416
	ds_read_b128 v[220:223], v1 offset:50144
	ds_read_b128 v[228:231], v15 offset:7904
	s_waitcnt lgkmcnt(8)
	v_mfma_f32_32x32x16_bf16 v[128:143], v[232:235], v[244:247], v[128:143]
	v_mfma_f32_32x32x16_bf16 v[112:127], v[232:235], v[248:251], v[112:127]
	v_mfma_f32_32x32x16_bf16 v[96:111], v[236:239], v[244:247], v[96:111]
	v_mfma_f32_32x32x16_bf16 v[80:95], v[236:239], v[248:251], v[80:95]
	ds_read_b128 v[244:247], v1 offset:16896
	ds_read_b128 v[232:235], v15 offset:8448
	ds_read_b128 v[248:251], v1 offset:50176
	ds_read_b128 v[236:239], v15 offset:7936
	s_waitcnt lgkmcnt(8)
	v_mfma_f32_32x32x16_bf16 v[128:143], v[10:13], v[2:5], v[128:143]
	v_mfma_f32_32x32x16_bf16 v[112:127], v[10:13], v[216:219], v[112:127]
	v_mfma_f32_32x32x16_bf16 v[96:111], v[224:227], v[2:5], v[96:111]
	v_mfma_f32_32x32x16_bf16 v[80:95], v[224:227], v[216:219], v[80:95]
	ds_read_b128 v[2:5], v1 offset:16928
	ds_read_b128 v[10:13], v15 offset:8480
	ds_read_b128 v[216:219], v1 offset:50208
	ds_read_b128 v[224:227], v15 offset:7968
	s_waitcnt lgkmcnt(8)
	v_mfma_f32_32x32x16_bf16 v[128:143], v[212:215], v[6:9], v[128:143]
	v_mfma_f32_32x32x16_bf16 v[112:127], v[212:215], v[220:223], v[112:127]
	v_mfma_f32_32x32x16_bf16 v[96:111], v[228:231], v[6:9], v[96:111]
	v_mfma_f32_32x32x16_bf16 v[80:95], v[228:231], v[220:223], v[80:95]
	ds_read_b128 v[6:9], v1 offset:16960
	ds_read_b128 v[212:215], v15 offset:8512
	ds_read_b128 v[220:223], v1 offset:50240
	ds_read_b128 v[228:231], v15 offset:8000
	s_waitcnt lgkmcnt(8)
	v_mfma_f32_32x32x16_bf16 v[128:143], v[232:235], v[244:247], v[128:143]
	v_mfma_f32_32x32x16_bf16 v[112:127], v[232:235], v[248:251], v[112:127]
	v_mfma_f32_32x32x16_bf16 v[96:111], v[236:239], v[244:247], v[96:111]
	v_mfma_f32_32x32x16_bf16 v[80:95], v[236:239], v[248:251], v[80:95]
	ds_read_b128 v[244:247], v1 offset:16992
	ds_read_b128 v[232:235], v15 offset:8544
	ds_read_b128 v[248:251], v1 offset:50272
	ds_read_b128 v[236:239], v15 offset:8032
	s_waitcnt lgkmcnt(8)
	v_mfma_f32_32x32x16_bf16 v[128:143], v[10:13], v[2:5], v[128:143]
	v_mfma_f32_32x32x16_bf16 v[112:127], v[10:13], v[216:219], v[112:127]
	v_mfma_f32_32x32x16_bf16 v[96:111], v[224:227], v[2:5], v[96:111]
	v_mfma_f32_32x32x16_bf16 v[80:95], v[224:227], v[216:219], v[80:95]
	ds_read_b128 v[2:5], v1 offset:17024
	ds_read_b128 v[10:13], v15 offset:8576
	ds_read_b128 v[216:219], v1 offset:50304
	ds_read_b128 v[224:227], v15 offset:8064
	s_waitcnt lgkmcnt(8)
	v_mfma_f32_32x32x16_bf16 v[128:143], v[212:215], v[6:9], v[128:143]
	v_mfma_f32_32x32x16_bf16 v[112:127], v[212:215], v[220:223], v[112:127]
	v_mfma_f32_32x32x16_bf16 v[96:111], v[228:231], v[6:9], v[96:111]
	v_mfma_f32_32x32x16_bf16 v[80:95], v[228:231], v[220:223], v[80:95]
	ds_read_b128 v[6:9], v1 offset:17056
	ds_read_b128 v[212:215], v15 offset:8608
	ds_read_b128 v[220:223], v1 offset:50336
	ds_read_b128 v[228:231], v15 offset:8096
	s_waitcnt lgkmcnt(8)
	v_mfma_f32_32x32x16_bf16 v[128:143], v[232:235], v[244:247], v[128:143]
	v_mfma_f32_32x32x16_bf16 v[112:127], v[232:235], v[248:251], v[112:127]
	v_mfma_f32_32x32x16_bf16 v[96:111], v[236:239], v[244:247], v[96:111]
	v_mfma_f32_32x32x16_bf16 v[80:95], v[236:239], v[248:251], v[80:95]
	ds_read_b128 v[244:247], v1 offset:17088
	ds_read_b128 v[232:235], v15 offset:8640
	ds_read_b128 v[248:251], v1 offset:50368
	ds_read_b128 v[236:239], v15 offset:8128
	s_waitcnt lgkmcnt(8)
	v_mfma_f32_32x32x16_bf16 v[128:143], v[10:13], v[2:5], v[128:143]
	v_mfma_f32_32x32x16_bf16 v[112:127], v[10:13], v[216:219], v[112:127]
	v_mfma_f32_32x32x16_bf16 v[96:111], v[224:227], v[2:5], v[96:111]
	v_mfma_f32_32x32x16_bf16 v[80:95], v[224:227], v[216:219], v[80:95]
	ds_read_b128 v[2:5], v1 offset:17120
	ds_read_b128 v[10:13], v15 offset:8672
	ds_read_b128 v[216:219], v1 offset:50400
	ds_read_b128 v[224:227], v15 offset:8160
	s_waitcnt lgkmcnt(8)
	v_mfma_f32_32x32x16_bf16 v[128:143], v[212:215], v[6:9], v[128:143]
	v_mfma_f32_32x32x16_bf16 v[112:127], v[212:215], v[220:223], v[112:127]
	v_mfma_f32_32x32x16_bf16 v[96:111], v[228:231], v[6:9], v[96:111]
	v_mfma_f32_32x32x16_bf16 v[80:95], v[228:231], v[220:223], v[80:95]
	ds_read_b128 v[6:9], v1 offset:17152
	ds_read_b128 v[212:215], v15 offset:8704
	ds_read_b128 v[220:223], v1 offset:50432
	ds_read_b128 v[228:231], v15 offset:8192
	s_waitcnt lgkmcnt(8)
	v_mfma_f32_32x32x16_bf16 v[128:143], v[232:235], v[244:247], v[128:143]
	v_mfma_f32_32x32x16_bf16 v[112:127], v[232:235], v[248:251], v[112:127]
	v_mfma_f32_32x32x16_bf16 v[96:111], v[236:239], v[244:247], v[96:111]
	v_mfma_f32_32x32x16_bf16 v[80:95], v[236:239], v[248:251], v[80:95]
	ds_read_b128 v[244:247], v1 offset:17184
	ds_read_b128 v[232:235], v15 offset:8736
	ds_read_b128 v[248:251], v1 offset:50464
	ds_read_b128 v[236:239], v15 offset:8224
	s_waitcnt lgkmcnt(8)
	v_mfma_f32_32x32x16_bf16 v[128:143], v[10:13], v[2:5], v[128:143]
	v_mfma_f32_32x32x16_bf16 v[112:127], v[10:13], v[216:219], v[112:127]
	v_mfma_f32_32x32x16_bf16 v[96:111], v[224:227], v[2:5], v[96:111]
	v_mfma_f32_32x32x16_bf16 v[80:95], v[224:227], v[216:219], v[80:95]
	ds_read_b128 v[2:5], v1 offset:17216
	ds_read_b128 v[10:13], v15 offset:8768
	ds_read_b128 v[216:219], v1 offset:50496
	ds_read_b128 v[224:227], v15 offset:8256
	s_waitcnt lgkmcnt(8)
	v_mfma_f32_32x32x16_bf16 v[128:143], v[212:215], v[6:9], v[128:143]
	v_mfma_f32_32x32x16_bf16 v[112:127], v[212:215], v[220:223], v[112:127]
	v_mfma_f32_32x32x16_bf16 v[96:111], v[228:231], v[6:9], v[96:111]
	v_mfma_f32_32x32x16_bf16 v[80:95], v[228:231], v[220:223], v[80:95]
	ds_read_b128 v[6:9], v1 offset:17248
	ds_read_b128 v[212:215], v15 offset:8800
	ds_read_b128 v[220:223], v1 offset:50528
	ds_read_b128 v[228:231], v15 offset:8288
	s_waitcnt lgkmcnt(8)
	v_mfma_f32_32x32x16_bf16 v[128:143], v[232:235], v[244:247], v[128:143]
	v_mfma_f32_32x32x16_bf16 v[112:127], v[232:235], v[248:251], v[112:127]
	v_mfma_f32_32x32x16_bf16 v[96:111], v[236:239], v[244:247], v[96:111]
	v_mfma_f32_32x32x16_bf16 v[80:95], v[236:239], v[248:251], v[80:95]
	ds_read_b128 v[244:247], v1 offset:17280
	ds_read_b128 v[232:235], v15 offset:8832
	ds_read_b128 v[248:251], v1 offset:50560
	ds_read_b128 v[236:239], v15 offset:8320
	s_waitcnt lgkmcnt(8)
	v_mfma_f32_32x32x16_bf16 v[128:143], v[10:13], v[2:5], v[128:143]
	v_mfma_f32_32x32x16_bf16 v[112:127], v[10:13], v[216:219], v[112:127]
	v_mfma_f32_32x32x16_bf16 v[96:111], v[224:227], v[2:5], v[96:111]
	v_mfma_f32_32x32x16_bf16 v[80:95], v[224:227], v[216:219], v[80:95]
	ds_read_b128 v[2:5], v1 offset:17312
	ds_read_b128 v[10:13], v15 offset:8864
	ds_read_b128 v[216:219], v1 offset:50592
	ds_read_b128 v[224:227], v15 offset:8352
	s_waitcnt lgkmcnt(8)
	v_mfma_f32_32x32x16_bf16 v[128:143], v[212:215], v[6:9], v[128:143]
	v_mfma_f32_32x32x16_bf16 v[112:127], v[212:215], v[220:223], v[112:127]
	v_mfma_f32_32x32x16_bf16 v[96:111], v[228:231], v[6:9], v[96:111]
	v_mfma_f32_32x32x16_bf16 v[80:95], v[228:231], v[220:223], v[80:95]
	ds_read_b128 v[6:9], v1 offset:17344
	ds_read_b128 v[212:215], v15 offset:8896
	ds_read_b128 v[220:223], v1 offset:50624
	ds_read_b128 v[228:231], v15 offset:8384
	s_waitcnt lgkmcnt(8)
	v_mfma_f32_32x32x16_bf16 v[128:143], v[232:235], v[244:247], v[128:143]
	v_mfma_f32_32x32x16_bf16 v[112:127], v[232:235], v[248:251], v[112:127]
	v_mfma_f32_32x32x16_bf16 v[96:111], v[236:239], v[244:247], v[96:111]
	v_mfma_f32_32x32x16_bf16 v[80:95], v[236:239], v[248:251], v[80:95]
	ds_read_b128 v[244:247], v1 offset:17376
	ds_read_b128 v[232:235], v15 offset:8928
	ds_read_b128 v[248:251], v1 offset:50656
	ds_read_b128 v[236:239], v15 offset:8416
	s_waitcnt lgkmcnt(8)
	v_mfma_f32_32x32x16_bf16 v[128:143], v[10:13], v[2:5], v[128:143]
	v_mfma_f32_32x32x16_bf16 v[112:127], v[10:13], v[216:219], v[112:127]
	v_mfma_f32_32x32x16_bf16 v[96:111], v[224:227], v[2:5], v[96:111]
	v_mfma_f32_32x32x16_bf16 v[80:95], v[224:227], v[216:219], v[80:95]
	ds_read_b128 v[2:5], v1 offset:17408
	ds_read_b128 v[10:13], v15 offset:8960
	ds_read_b128 v[216:219], v1 offset:50688
	ds_read_b128 v[224:227], v15 offset:8448
	s_waitcnt lgkmcnt(8)
	v_mfma_f32_32x32x16_bf16 v[128:143], v[212:215], v[6:9], v[128:143]
	v_mfma_f32_32x32x16_bf16 v[112:127], v[212:215], v[220:223], v[112:127]
	v_mfma_f32_32x32x16_bf16 v[96:111], v[228:231], v[6:9], v[96:111]
	v_mfma_f32_32x32x16_bf16 v[80:95], v[228:231], v[220:223], v[80:95]
	ds_read_b128 v[6:9], v1 offset:17440
	ds_read_b128 v[212:215], v15 offset:8992
	ds_read_b128 v[220:223], v1 offset:50720
	ds_read_b128 v[228:231], v15 offset:8480
	s_waitcnt lgkmcnt(8)
	v_mfma_f32_32x32x16_bf16 v[128:143], v[232:235], v[244:247], v[128:143]
	v_mfma_f32_32x32x16_bf16 v[112:127], v[232:235], v[248:251], v[112:127]
	v_mfma_f32_32x32x16_bf16 v[96:111], v[236:239], v[244:247], v[96:111]
	v_mfma_f32_32x32x16_bf16 v[80:95], v[236:239], v[248:251], v[80:95]
	ds_read_b128 v[244:247], v1 offset:17472
	ds_read_b128 v[232:235], v15 offset:9024
	ds_read_b128 v[248:251], v1 offset:50752
	ds_read_b128 v[236:239], v15 offset:8512
	s_waitcnt lgkmcnt(8)
	v_mfma_f32_32x32x16_bf16 v[128:143], v[10:13], v[2:5], v[128:143]
	v_mfma_f32_32x32x16_bf16 v[112:127], v[10:13], v[216:219], v[112:127]
	v_mfma_f32_32x32x16_bf16 v[96:111], v[224:227], v[2:5], v[96:111]
	v_mfma_f32_32x32x16_bf16 v[80:95], v[224:227], v[216:219], v[80:95]
	ds_read_b128 v[2:5], v1 offset:17504
	ds_read_b128 v[10:13], v15 offset:9056
	ds_read_b128 v[216:219], v1 offset:50784
	ds_read_b128 v[224:227], v15 offset:8544
	s_waitcnt lgkmcnt(8)
	v_mfma_f32_32x32x16_bf16 v[128:143], v[212:215], v[6:9], v[128:143]
	v_mfma_f32_32x32x16_bf16 v[112:127], v[212:215], v[220:223], v[112:127]
	v_mfma_f32_32x32x16_bf16 v[96:111], v[228:231], v[6:9], v[96:111]
	v_mfma_f32_32x32x16_bf16 v[80:95], v[228:231], v[220:223], v[80:95]
	ds_read_b128 v[6:9], v1 offset:17536
	ds_read_b128 v[212:215], v15 offset:9088
	ds_read_b128 v[220:223], v1 offset:50816
	ds_read_b128 v[228:231], v15 offset:8576
	s_waitcnt lgkmcnt(8)
	v_mfma_f32_32x32x16_bf16 v[128:143], v[232:235], v[244:247], v[128:143]
	v_mfma_f32_32x32x16_bf16 v[112:127], v[232:235], v[248:251], v[112:127]
	v_mfma_f32_32x32x16_bf16 v[96:111], v[236:239], v[244:247], v[96:111]
	v_mfma_f32_32x32x16_bf16 v[80:95], v[236:239], v[248:251], v[80:95]
	ds_read_b128 v[244:247], v1 offset:17568
	ds_read_b128 v[232:235], v15 offset:9120
	ds_read_b128 v[248:251], v1 offset:50848
	ds_read_b128 v[236:239], v15 offset:8608
	s_waitcnt lgkmcnt(8)
	v_mfma_f32_32x32x16_bf16 v[128:143], v[10:13], v[2:5], v[128:143]
	v_mfma_f32_32x32x16_bf16 v[112:127], v[10:13], v[216:219], v[112:127]
	v_mfma_f32_32x32x16_bf16 v[96:111], v[224:227], v[2:5], v[96:111]
	v_mfma_f32_32x32x16_bf16 v[80:95], v[224:227], v[216:219], v[80:95]
	ds_read_b128 v[2:5], v1 offset:17600
	ds_read_b128 v[10:13], v15 offset:9152
	ds_read_b128 v[216:219], v1 offset:50880
	ds_read_b128 v[224:227], v15 offset:8640
	s_waitcnt lgkmcnt(8)
	v_mfma_f32_32x32x16_bf16 v[128:143], v[212:215], v[6:9], v[128:143]
	v_mfma_f32_32x32x16_bf16 v[112:127], v[212:215], v[220:223], v[112:127]
	v_mfma_f32_32x32x16_bf16 v[96:111], v[228:231], v[6:9], v[96:111]
	v_mfma_f32_32x32x16_bf16 v[80:95], v[228:231], v[220:223], v[80:95]
	ds_read_b128 v[6:9], v1 offset:17632
	ds_read_b128 v[212:215], v15 offset:9184
	ds_read_b128 v[220:223], v1 offset:50912
	ds_read_b128 v[228:231], v15 offset:8672
	s_waitcnt lgkmcnt(8)
	v_mfma_f32_32x32x16_bf16 v[128:143], v[232:235], v[244:247], v[128:143]
	v_mfma_f32_32x32x16_bf16 v[112:127], v[232:235], v[248:251], v[112:127]
	v_mfma_f32_32x32x16_bf16 v[96:111], v[236:239], v[244:247], v[96:111]
	v_mfma_f32_32x32x16_bf16 v[80:95], v[236:239], v[248:251], v[80:95]
	s_waitcnt lgkmcnt(4)
	v_mfma_f32_32x32x16_bf16 v[128:143], v[10:13], v[2:5], v[128:143]
	v_mfma_f32_32x32x16_bf16 v[112:127], v[10:13], v[216:219], v[112:127]
	v_mfma_f32_32x32x16_bf16 v[96:111], v[224:227], v[2:5], v[96:111]
	v_mfma_f32_32x32x16_bf16 v[80:95], v[224:227], v[216:219], v[80:95]
	s_waitcnt lgkmcnt(0)
	v_mfma_f32_32x32x16_bf16 v[128:143], v[212:215], v[6:9], v[128:143]
	v_mfma_f32_32x32x16_bf16 v[112:127], v[212:215], v[220:223], v[112:127]
	v_mfma_f32_32x32x16_bf16 v[96:111], v[228:231], v[6:9], v[96:111]
	v_mfma_f32_32x32x16_bf16 v[80:95], v[228:231], v[220:223], v[80:95]
	s_mov_b64 s[30:31], 0
